# attention K/V staging: one barrier per KV tile (K half written to LDS before the barrier, V half after it; second barrier dropped)
# baseline (speedup 1.0000x reference)
; #define SBAR() __builtin_amdgcn_sched_barrier(0)
; #define SWRITE(b, i) do { *(bf16x8*)(V_lds + (b) * SHM_V + vst0) = sr_[i].vs0;          \
;     *(bf16x8*)(V_lds + (b) * SHM_V + vst1) = sr_[i].vs1; int kc = sc * 2;               \
;     *(bf16x8*)(K_lds + (b) * SHM_K + KSWZ(sr, kc)) = sr_[i].ks0;                       \
;     *(bf16x8*)(K_lds + (b) * SHM_K + KSWZ(32 + sr, kc)) = sr_[i].ks1; } while (0)
; #define SWAIT() asm volatile("s_waitcnt vmcnt(0)" ::: "memory")
; #define RESC(a) do { if (__any((a) < 1.f)) { if (hi == 0) al_l[r32] = (a); asm volatile("s_waitcnt lgkmcnt(0)" ::: "memory"); \
;     _Pragma("unroll") for (int d = 0; d < 4; ++d) _Pragma("unroll") for (int r = 0; r < 16; ++r) o[d][r] *= al_l[crow(r, hi)]; } } while (0)
; DI void attn_unit(const bf16_t* __restrict__ Qb, const bf16_t* __restrict__ Kh, const bf16_t* __restrict__ Vh, bf16_t* __restrict__ Ob, const float* __restrict__ onw, int seq, char* lds) {
;     ...
;         __syncthreads(); SWAIT(); SWRITE(0, SE);
;         RESC(alB); __syncthreads();
;         SBAR(); qkt(pA0, pA1, K_lds, qr, -m_reg, r32, hi);
.LBB0_581:
	s_waitcnt vmcnt(0)
	ds_write_b128 v204, v[68:71] offset:32768
	ds_write_b128 v205, v[72:75] offset:32768
	v_cmp_gt_f32_e32 vcc, 1.0, v154
	s_waitcnt lgkmcnt(0)
	s_barrier
	ds_write_b128 v206, v[64:67]
	ds_write_b128 v207, v[76:79]
	s_cbranch_vccz .LBB0_585
	s_and_saveexec_b64 s[14:15], s[2:3]
	ds_write_b32 v172, v154 offset:128
	s_or_b64 exec, exec, s[14:15]
	s_waitcnt lgkmcnt(0)
	v_add_u32_e32 v76, v171, v184
	ds_read_b128 v[64:67], v76 offset:224
	ds_read_b128 v[68:71], v76 offset:192
	ds_read_b128 v[72:75], v76 offset:160
	ds_read_b128 v[76:79], v76 offset:128
	s_waitcnt lgkmcnt(3)
	v_pk_mul_f32 v[12:13], v[12:13], v[64:65]
	s_waitcnt lgkmcnt(2)
	v_pk_mul_f32 v[8:9], v[8:9], v[68:69]
	s_waitcnt lgkmcnt(1)
	v_pk_mul_f32 v[4:5], v[4:5], v[72:73]
	v_pk_mul_f32 v[14:15], v[14:15], v[66:67]
	v_pk_mul_f32 v[10:11], v[10:11], v[70:71]
	v_pk_mul_f32 v[6:7], v[6:7], v[74:75]
	s_waitcnt lgkmcnt(0)
	v_pk_mul_f32 v[2:3], v[2:3], v[78:79]
	v_pk_mul_f32 v[0:1], v[0:1], v[76:77]
	v_pk_mul_f32 v[60:61], v[60:61], v[64:65]
	v_pk_mul_f32 v[56:57], v[56:57], v[68:69]
	v_pk_mul_f32 v[52:53], v[52:53], v[72:73]
	v_pk_mul_f32 v[62:63], v[62:63], v[66:67]
	v_pk_mul_f32 v[58:59], v[58:59], v[70:71]
	v_pk_mul_f32 v[54:55], v[54:55], v[74:75]
	v_pk_mul_f32 v[50:51], v[50:51], v[78:79]
	v_pk_mul_f32 v[48:49], v[48:49], v[76:77]
	v_pk_mul_f32 v[28:29], v[28:29], v[64:65]
	v_pk_mul_f32 v[24:25], v[24:25], v[68:69]
	v_pk_mul_f32 v[20:21], v[20:21], v[72:73]
	v_pk_mul_f32 v[30:31], v[30:31], v[66:67]
	v_pk_mul_f32 v[26:27], v[26:27], v[70:71]
	v_pk_mul_f32 v[22:23], v[22:23], v[74:75]
	v_pk_mul_f32 v[18:19], v[18:19], v[78:79]
	v_pk_mul_f32 v[16:17], v[16:17], v[76:77]
	v_pk_mul_f32 v[44:45], v[44:45], v[64:65]
	v_pk_mul_f32 v[40:41], v[40:41], v[68:69]
	v_pk_mul_f32 v[36:37], v[36:37], v[72:73]
	v_pk_mul_f32 v[46:47], v[46:47], v[66:67]
	v_pk_mul_f32 v[42:43], v[42:43], v[70:71]
	v_pk_mul_f32 v[38:39], v[38:39], v[74:75]
	v_pk_mul_f32 v[34:35], v[34:35], v[78:79]
	v_pk_mul_f32 v[32:33], v[32:33], v[76:77]
.LBB0_585:
	ds_read_b128 v[218:221], v183 offset:32768
	ds_read_b128 v[222:225], v183 offset:40960
	v_xor_b32_e32 v64, 0x80000000, v215
	v_mov_b32_e32 v65, v64
	v_mov_b32_e32 v66, v64
	v_mov_b32_e32 v67, v64
	v_mov_b32_e32 v68, v64
	v_mov_b32_e32 v69, v64
	v_mov_b32_e32 v70, v64
	v_mov_b32_e32 v71, v64
	v_mov_b32_e32 v72, v64
	v_mov_b32_e32 v73, v64
	v_mov_b32_e32 v74, v64
	v_mov_b32_e32 v75, v64
	v_mov_b32_e32 v76, v64
	v_mov_b32_e32 v77, v64
	v_mov_b32_e32 v78, v64
	v_mov_b32_e32 v79, v64
	v_add_f32_e32 v168, 0, v144
	v_add_f32_e32 v168, v145, v168
	s_waitcnt lgkmcnt(1)
	v_mfma_f32_32x32x16_bf16 v[96:111], v[218:221], v[140:143], v[64:79]
	v_add_f32_e32 v168, v158, v168
	v_add_f32_e32 v168, v159, v168
	v_add_f32_e32 v168, v146, v168
	v_add_f32_e32 v168, v147, v168
	v_add_f32_e32 v168, v156, v168
	v_add_f32_e32 v168, v157, v168
	v_add_f32_e32 v168, v166, v168
	s_waitcnt lgkmcnt(0)
	v_mfma_f32_32x32x16_bf16 v[64:79], v[222:225], v[140:143], v[64:79]
	ds_read_b128 v[218:221], v208 offset:32768
	ds_read_b128 v[222:225], v208 offset:40960
	v_add_f32_e32 v168, v167, v168
	v_add_f32_e32 v168, v162, v168
	v_add_f32_e32 v168, v163, v168
	v_exp_f32_e32 v80, v80
	v_add_f32_e32 v168, v164, v168
	v_exp_f32_e32 v81, v81
	s_waitcnt lgkmcnt(0)
	v_mfma_f32_32x32x16_bf16 v[64:79], v[222:225], v[136:139], v[64:79]
	v_add_f32_e32 v168, v165, v168
	v_exp_f32_e32 v82, v82
	v_add_f32_e32 v168, v160, v168
	v_exp_f32_e32 v83, v83
	v_add_f32_e32 v168, v161, v168
	v_exp_f32_e32 v84, v84
	v_add_f32_e32 v168, v80, v168
	v_mfma_f32_32x32x16_bf16 v[96:111], v[218:221], v[136:139], v[96:111]
	ds_read_b128 v[218:221], v209 offset:32768
	ds_read_b128 v[222:225], v209 offset:40960
	v_exp_f32_e32 v85, v85
	v_add_f32_e32 v168, v81, v168
	v_exp_f32_e32 v86, v86
	v_add_f32_e32 v168, v82, v168
	v_exp_f32_e32 v87, v87
	v_add_f32_e32 v168, v83, v168
	s_waitcnt lgkmcnt(0)
	v_mfma_f32_32x32x16_bf16 v[64:79], v[222:225], v[132:135], v[64:79]
	v_exp_f32_e32 v88, v88
	v_add_f32_e32 v168, v84, v168
	v_exp_f32_e32 v89, v89
	v_add_f32_e32 v168, v85, v168
	v_exp_f32_e32 v90, v90
	v_add_f32_e32 v168, v86, v168
	v_exp_f32_e32 v91, v91
	v_mfma_f32_32x32x16_bf16 v[96:111], v[218:221], v[132:135], v[96:111]
	ds_read_b128 v[218:221], v210 offset:32768
	ds_read_b128 v[222:225], v210 offset:40960
	v_add_f32_e32 v168, v87, v168
	v_exp_f32_e32 v92, v92
	v_add_f32_e32 v168, v88, v168
	v_exp_f32_e32 v93, v93
	v_add_f32_e32 v168, v89, v168
	v_exp_f32_e32 v94, v94
	s_waitcnt lgkmcnt(0)
	v_mfma_f32_32x32x16_bf16 v[64:79], v[222:225], v[128:131], v[64:79]
	v_add_f32_e32 v168, v90, v168
	v_exp_f32_e32 v95, v95
	v_add_f32_e32 v168, v91, v168
	v_add_f32_e32 v168, v92, v168
	v_add_f32_e32 v168, v93, v168
	v_add_f32_e32 v168, v94, v168
	v_mfma_f32_32x32x16_bf16 v[96:111], v[218:221], v[128:131], v[96:111]
	ds_read_b128 v[218:221], v211 offset:32768
	ds_read_b128 v[222:225], v211 offset:40960
	s_waitcnt lgkmcnt(0)
	v_mfma_f32_32x32x16_bf16 v[64:79], v[222:225], v[124:127], v[64:79]
	v_mfma_f32_32x32x16_bf16 v[96:111], v[218:221], v[124:127], v[96:111]
	ds_read_b128 v[218:221], v212 offset:32768
	ds_read_b128 v[222:225], v212 offset:40960
	s_waitcnt lgkmcnt(0)
	v_mfma_f32_32x32x16_bf16 v[64:79], v[222:225], v[120:123], v[64:79]
	v_mfma_f32_32x32x16_bf16 v[96:111], v[218:221], v[120:123], v[96:111]
	ds_read_b128 v[218:221], v213 offset:32768
	ds_read_b128 v[222:225], v213 offset:40960
	s_waitcnt lgkmcnt(0)
; DI void finishSM(f32x16& p0, f32x16& p1, float alpha, float& l_reg, bf16x8& pa0, bf16x8& pa1, bf16x8& pa2, bf16x8& pa3) {
; #pragma unroll
;     for (int r = 0; r < 16; ++r) p1[r] = __builtin_amdgcn_exp2f(p1[r]);
;     float ps = 0;
; #pragma unroll
;     for (int r = 0; r < 16; ++r) ps += p0[r];
; #pragma unroll
;     for (int r = 0; r < 16; ++r) ps += p1[r];
;     { auto rr = __builtin_amdgcn_permlane32_swap(__float_as_uint(ps), __float_as_uint(ps), false, false);
;       ps = __uint_as_float(rr[0]) + __uint_as_float(rr[1]); }
;     l_reg = l_reg * alpha + ps;
;     ...
;     PK4(p0, 0, pa0); PK4(p0, 8, pa1); PK4(p1, 0, pa2); PK4(p1, 8, pa3);
;     ...
; }
; DI void qkt(f32x16& p0, f32x16& p1, const char* Ks, const bf16x8* qr, float negm, int r32, int hi) {
; #pragma unroll
;     for (int i = 0; i < 16; ++i) { p0[i] = negm; p1[i] = negm; }
; #pragma unroll
;     for (int d0 = 0; d0 < 8; ++d0) { const int cb = (d0 * 16 + hi * 8) * 2;
;         bf16x8 b0 = *(const bf16x8*)(Ks + KSWZ(r32, cb));
;         bf16x8 b1 = *(const bf16x8*)(Ks + KSWZ(32 + r32, cb));
;         p0 = MFMA32(b0, qr[d0], p0);
;         p1 = MFMA32(b1, qr[d0], p1); }
; }
; DI int v_st(int k, int c) { const int kk = (k & ~0xC) | ((k & 4) << 1) | ((k & 8) >> 1); return ((kk >> 3) * 4 + (c >> 5)) * 512 + ((kk & 7) * 32 + (c & 31)) * 2; }
; DI int v_rd_base(int lane) { return ((lane & 3) << 3) | (((lane >> 2) & 3) << 6) | (((lane >> 4) & 1) << 5) | (((lane >> 5) & 1) << 8); }
; template <int OFF> DI s16x4 tr_read(int vb) { s16x4 r; asm volatile("ds_read_b64_tr_b16 %0, %1 offset:%2" : "=&v"(r) : "v"(vb), "i"(OFF) : "memory"); return r; }
; template <int D0> DI void pv_one(f32x16& od, int vb, bf16x8 pa0, bf16x8 pa1, bf16x8 pa2, bf16x8 pa3) {
;     const s16x4 l0 = tr_read<v_rd_off(D0, 0, 0)>(vb), h0 = tr_read<v_rd_off(D0, 0, 1)>(vb), l1 = tr_read<v_rd_off(D0, 1, 0)>(vb), h1 = tr_read<v_rd_off(D0, 1, 1)>(vb);
;     const s16x4 l2 = tr_read<v_rd_off(D0, 2, 0)>(vb), h2 = tr_read<v_rd_off(D0, 2, 1)>(vb), l3 = tr_read<v_rd_off(D0, 3, 0)>(vb), h3 = tr_read<v_rd_off(D0, 3, 1)>(vb);
;     asm volatile("s_waitcnt lgkmcnt(0)" ::: "memory"); SBAR();
;     ...
;     od = MFMA32(pa0, PK(l0, h0), od);
;     od = MFMA32(pa1, PK(l1, h1), od);
;     od = MFMA32(pa2, PK(l2, h2), od);
;     od = MFMA32(pa3, PK(l3, h3), od);
;     ...
; }
; DI float pv_d0_sm(f32x16* o, int vb, bf16x8 pa0, bf16x8 pa1, bf16x8 pa2, bf16x8 pa3, f32x16& q0, f32x16& q1) {
	v_mfma_f32_32x32x16_bf16 v[64:79], v[222:225], v[116:119], v[64:79]
	v_mfma_f32_32x32x16_bf16 v[96:111], v[218:221], v[116:119], v[96:111]
	ds_read_b128 v[218:221], v214 offset:32768
	ds_read_b128 v[222:225], v214 offset:40960
	v_cvt_pk_bf16_f32 v144, v144, v145
	v_cvt_pk_bf16_f32 v145, v158, v159
	v_cvt_pk_bf16_f32 v146, v146, v147
	v_cvt_pk_bf16_f32 v147, v156, v157
	s_nop 0
	v_permlane32_swap_b32_e32 v144, v146
	s_waitcnt lgkmcnt(0)
	v_mfma_f32_32x32x16_bf16 v[64:79], v[222:225], v[112:115], v[64:79]
	v_permlane32_swap_b32_e32 v145, v147
	v_cvt_pk_bf16_f32 v222, v166, v167
	v_cvt_pk_bf16_f32 v223, v162, v163
	v_cvt_pk_bf16_f32 v224, v164, v165
	v_cvt_pk_bf16_f32 v225, v160, v161
	v_cvt_pk_bf16_f32 v226, v80, v81
	v_mfma_f32_32x32x16_bf16 v[96:111], v[218:221], v[112:115], v[96:111]
	v_add_f32_e32 v218, v95, v168
	v_mov_b32_e32 v219, v218
	s_nop 1
	v_permlane32_swap_b32_e32 v218, v219
	v_cvt_pk_bf16_f32 v227, v82, v83
	v_cvt_pk_bf16_f32 v228, v84, v85
	v_cvt_pk_bf16_f32 v229, v86, v87
	v_cvt_pk_bf16_f32 v230, v88, v89
	v_cvt_pk_bf16_f32 v231, v90, v91
	v_cvt_pk_bf16_f32 v232, v92, v93
	v_cvt_pk_bf16_f32 v233, v94, v95
	v_permlane32_swap_b32_e32 v222, v224
	v_permlane32_swap_b32_e32 v223, v225
	v_permlane32_swap_b32_e32 v226, v228
	v_permlane32_swap_b32_e32 v227, v229
	v_permlane32_swap_b32_e32 v230, v232
	v_permlane32_swap_b32_e32 v231, v233
	v_add_co_u32_e32 v84, vcc, s83, v152
	s_nop 1
	v_addc_co_u32_e32 v85, vcc, 0, v153, vcc
	v_add_co_u32_e32 v88, vcc, s84, v152
	s_nop 1
	v_addc_co_u32_e32 v89, vcc, 0, v153, vcc
	global_load_dwordx4 v[80:83], v[84:85], off offset:512
	s_nop 0
	global_load_dwordx4 v[84:87], v[84:85], off
	s_nop 0
	global_load_dwordx4 v[92:95], v[88:89], off offset:512
	s_nop 0
	global_load_dwordx4 v[88:91], v[88:89], off
	ds_read_b64_tr_b16 v[156:157], v174 offset:0
	ds_read_b64_tr_b16 v[158:159], v174 offset:0x800
	ds_read_b64_tr_b16 v[160:161], v174 offset:0x1000
	ds_read_b64_tr_b16 v[162:163], v174 offset:0x1800
	ds_read_b64_tr_b16 v[164:165], v174 offset:0x2000
	ds_read_b64_tr_b16 v[166:167], v174 offset:0x2800
	ds_read_b64_tr_b16 v[234:235], v174 offset:0x3000
	ds_read_b64_tr_b16 v[236:237], v174 offset:0x3800
	s_waitcnt lgkmcnt(0)
	s_nop 0
	v_mfma_f32_32x32x16_bf16 v[0:15], v[144:147], v[156:159], v[0:15]
	v_max_f32_e32 v156, v97, v97
	v_max_f32_e32 v157, v96, v96
	v_max_f32_e32 v156, v157, v156
	v_max3_f32 v156, v156, v98, v99
	v_max3_f32 v156, v156, v100, v101
	v_max3_f32 v156, v156, v102, v103
	v_max3_f32 v156, v156, v104, v105
	v_mfma_f32_32x32x16_bf16 v[0:15], v[222:225], v[160:163], v[0:15]
	v_max3_f32 v156, v156, v106, v107
	v_max3_f32 v158, v156, v108, v109
	ds_read_b64_tr_b16 v[156:157], v174 offset:0x200
	v_max3_f32 v168, v158, v110, v111
	ds_read_b64_tr_b16 v[158:159], v174 offset:0xa00
	ds_read_b64_tr_b16 v[160:161], v174 offset:0x1200
	ds_read_b64_tr_b16 v[162:163], v174 offset:0x1a00
	v_mfma_f32_32x32x16_bf16 v[0:15], v[226:229], v[164:167], v[0:15]
	ds_read_b64_tr_b16 v[164:165], v174 offset:0x2200
	ds_read_b64_tr_b16 v[166:167], v174 offset:0x2a00
	ds_read_b64_tr_b16 v[238:239], v174 offset:0x3200
	ds_read_b64_tr_b16 v[240:241], v174 offset:0x3a00
	s_waitcnt lgkmcnt(0)
	v_mfma_f32_32x32x16_bf16 v[0:15], v[230:233], v[234:237], v[0:15]
	v_mfma_f32_32x32x16_bf16 v[48:63], v[144:147], v[156:159], v[48:63]
	v_max3_f32 v168, v168, v64, v65
	v_max3_f32 v156, v168, v66, v67
	v_max3_f32 v156, v156, v68, v69
	v_max3_f32 v156, v156, v70, v71
	v_max3_f32 v156, v156, v72, v73
	v_max3_f32 v156, v156, v74, v75
	v_max3_f32 v156, v156, v76, v77
	v_mfma_f32_32x32x16_bf16 v[48:63], v[222:225], v[160:163], v[48:63]
	v_max3_f32 v156, v156, v78, v79
	v_mov_b32_e32 v157, v156
	s_nop 1
	v_permlane32_swap_b32_e32 v156, v157
	v_max_f32_e32 v157, v157, v157
	v_max_f32_e32 v156, v156, v156
	v_max_f32_e32 v220, v156, v157
	v_mfma_f32_32x32x16_bf16 v[48:63], v[226:229], v[164:167], v[48:63]
	ds_read_b64_tr_b16 v[156:157], v174 offset:0x400
	ds_read_b64_tr_b16 v[158:159], v174 offset:0xc00
	ds_read_b64_tr_b16 v[160:161], v174 offset:0x1400
	ds_read_b64_tr_b16 v[162:163], v174 offset:0x1c00
	ds_read_b64_tr_b16 v[234:235], v174 offset:0x2400
	ds_read_b64_tr_b16 v[236:237], v174 offset:0x2c00
	ds_read_b64_tr_b16 v[242:243], v174 offset:0x3400
	v_mfma_f32_32x32x16_bf16 v[48:63], v[230:233], v[238:241], v[48:63]
	ds_read_b64_tr_b16 v[244:245], v174 offset:0x3c00
	s_waitcnt lgkmcnt(0)
	v_mfma_f32_32x32x16_bf16 v[16:31], v[144:147], v[156:159], v[16:31]
	v_exp_f32_e32 v166, v96
	v_exp_f32_e32 v167, v97
	ds_read_b64_tr_b16 v[96:97], v174 offset:0x600
	v_exp_f32_e32 v158, v100
	v_exp_f32_e32 v159, v101
	v_exp_f32_e32 v156, v102
	v_exp_f32_e32 v157, v103
	v_mfma_f32_32x32x16_bf16 v[16:31], v[222:225], v[160:163], v[16:31]
	v_exp_f32_e32 v162, v98
	v_exp_f32_e32 v163, v99
	ds_read_b64_tr_b16 v[98:99], v174 offset:0xe00
	ds_read_b64_tr_b16 v[100:101], v174 offset:0x1600
	ds_read_b64_tr_b16 v[102:103], v174 offset:0x1e00
	v_mfma_f32_32x32x16_bf16 v[16:31], v[226:229], v[234:237], v[16:31]
	ds_read_b64_tr_b16 v[234:235], v174 offset:0x2600
	ds_read_b64_tr_b16 v[236:237], v174 offset:0x2e00
	ds_read_b64_tr_b16 v[238:239], v174 offset:0x3600
	ds_read_b64_tr_b16 v[240:241], v174 offset:0x3e00
	s_waitcnt lgkmcnt(0)
	v_mfma_f32_32x32x16_bf16 v[16:31], v[230:233], v[242:245], v[16:31]
	v_mfma_f32_32x32x16_bf16 v[32:47], v[144:147], v[96:99], v[32:47]
	v_exp_f32_e32 v168, v104
	v_exp_f32_e32 v169, v105
	v_exp_f32_e32 v164, v106
	v_exp_f32_e32 v165, v107
	v_exp_f32_e32 v160, v108
	v_exp_f32_e32 v161, v109
	v_exp_f32_e32 v146, v110
	v_mfma_f32_32x32x16_bf16 v[32:47], v[222:225], v[100:103], v[32:47]
	v_exp_f32_e32 v147, v111
	v_cmp_ge_f32_e32 vcc, s82, v220
	s_cmp_eq_u64 vcc, exec
	v_mfma_f32_32x32x16_bf16 v[32:47], v[226:229], v[234:237], v[32:47]
	v_mfma_f32_32x32x16_bf16 v[32:47], v[230:233], v[238:241], v[32:47]
	s_cbranch_scc0 .LBB0_594
	v_mov_b32_e32 v144, 1.0
; #define SWRITE(b, i) do { *(bf16x8*)(V_lds + (b) * SHM_V + vst0) = sr_[i].vs0;          \
;     *(bf16x8*)(V_lds + (b) * SHM_V + vst1) = sr_[i].vs1; int kc = sc * 2;               \
;     *(bf16x8*)(K_lds + (b) * SHM_K + KSWZ(sr, kc)) = sr_[i].ks0;                       \
;     *(bf16x8*)(K_lds + (b) * SHM_K + KSWZ(32 + sr, kc)) = sr_[i].ks1; } while (0)
; #define SWAIT() asm volatile("s_waitcnt vmcnt(0)" ::: "memory")
; #define RESC(a) do { if (__any((a) < 1.f)) { if (hi == 0) al_l[r32] = (a); asm volatile("s_waitcnt lgkmcnt(0)" ::: "memory"); \
;     _Pragma("unroll") for (int d = 0; d < 4; ++d) _Pragma("unroll") for (int r = 0; r < 16; ++r) o[d][r] *= al_l[crow(r, hi)]; } } while (0)
; DI void attn_unit(const bf16_t* __restrict__ Qb, const bf16_t* __restrict__ Kh, const bf16_t* __restrict__ Vh, bf16_t* __restrict__ Ob, const float* __restrict__ onw, int seq, char* lds) {
;     ...
;         __syncthreads(); SWAIT(); SWRITE(1, SO);
;         RESC(alA); __syncthreads();
;     }
.LBB0_587:
	s_waitcnt vmcnt(0)
	ds_write_b128 v204, v[84:87] offset:49152
	ds_write_b128 v205, v[88:91] offset:49152
	v_cmp_gt_f32_e32 vcc, 1.0, v144
	s_waitcnt lgkmcnt(0)
	s_barrier
	ds_write_b128 v206, v[80:83] offset:16384
	ds_write_b128 v207, v[92:95] offset:16384
	s_cbranch_vccz .LBB0_591
	s_and_saveexec_b64 s[14:15], s[2:3]
	ds_write_b32 v172, v144 offset:128
	s_or_b64 exec, exec, s[14:15]
	s_waitcnt lgkmcnt(0)
	v_add_u32_e32 v92, v171, v184
	ds_read_b128 v[80:83], v92 offset:224
	ds_read_b128 v[84:87], v92 offset:192
	ds_read_b128 v[88:91], v92 offset:160
	ds_read_b128 v[92:95], v92 offset:128
	s_waitcnt lgkmcnt(3)
	v_pk_mul_f32 v[12:13], v[12:13], v[80:81]
	s_waitcnt lgkmcnt(2)
	v_pk_mul_f32 v[8:9], v[8:9], v[84:85]
	s_waitcnt lgkmcnt(1)
	v_pk_mul_f32 v[4:5], v[4:5], v[88:89]
	v_pk_mul_f32 v[14:15], v[14:15], v[82:83]
	v_pk_mul_f32 v[10:11], v[10:11], v[86:87]
	v_pk_mul_f32 v[6:7], v[6:7], v[90:91]
	s_waitcnt lgkmcnt(0)
	v_pk_mul_f32 v[2:3], v[2:3], v[94:95]
	v_pk_mul_f32 v[0:1], v[0:1], v[92:93]
	v_pk_mul_f32 v[60:61], v[60:61], v[80:81]
	v_pk_mul_f32 v[56:57], v[56:57], v[84:85]
	v_pk_mul_f32 v[52:53], v[52:53], v[88:89]
	v_pk_mul_f32 v[62:63], v[62:63], v[82:83]
	v_pk_mul_f32 v[58:59], v[58:59], v[86:87]
	v_pk_mul_f32 v[54:55], v[54:55], v[90:91]
	v_pk_mul_f32 v[50:51], v[50:51], v[94:95]
	v_pk_mul_f32 v[48:49], v[48:49], v[92:93]
	v_pk_mul_f32 v[28:29], v[28:29], v[80:81]
	v_pk_mul_f32 v[24:25], v[24:25], v[84:85]
	v_pk_mul_f32 v[20:21], v[20:21], v[88:89]
	v_pk_mul_f32 v[30:31], v[30:31], v[82:83]
	v_pk_mul_f32 v[26:27], v[26:27], v[86:87]
	v_pk_mul_f32 v[22:23], v[22:23], v[90:91]
	v_pk_mul_f32 v[18:19], v[18:19], v[94:95]
	v_pk_mul_f32 v[16:17], v[16:17], v[92:93]
	v_pk_mul_f32 v[44:45], v[44:45], v[80:81]
	v_pk_mul_f32 v[40:41], v[40:41], v[84:85]
	v_pk_mul_f32 v[36:37], v[36:37], v[88:89]
	v_pk_mul_f32 v[46:47], v[46:47], v[82:83]
	v_pk_mul_f32 v[42:43], v[42:43], v[86:87]
	v_pk_mul_f32 v[38:39], v[38:39], v[90:91]
	v_pk_mul_f32 v[34:35], v[34:35], v[94:95]
	v_pk_mul_f32 v[32:33], v[32:33], v[92:93]
.LBB0_591:
	v_add_f32_e32 v80, v216, v217
	v_fmac_f32_e32 v80, v150, v173
	v_add_f32_e32 v173, v218, v219
	s_add_i32 s42, s42, 2
	v_fmac_f32_e32 v173, v80, v154
	s_cmp_ge_u32 s42, s97
	v_lshl_add_u64 v[152:153], v[152:153], 0, s[60:61]
	s_cbranch_scc1 .LBB0_595
	v_mov_b32_e32 v150, v144
	s_branch .LBB0_580
